# EpiGU SwiGLU epilogue: scalar silu chains replaced by v_pk_mul_f32 on accumulator pairs (same op order), store-data WAR repadded
# baseline (speedup 1.0000x reference)
; __device__ __forceinline__ unsigned pk2(float lo, float hi) { unsigned r; asm volatile("v_cvt_pk_bf16_f32 %0, %1, %2" : "=v"(r) : "v"(lo), "v"(hi)); return r; }
; __device__ __forceinline__ float siluf_(float x) { return x * sigmoidf_(x); }
;     __device__ __forceinline__ void operator()(const f32x4 (&acc)[2][2][4][2], const pg8::Unit& u, int wr, int wc, int fr, int fq) const {
;     ...
;                 bf16_t* rowp = H + (size_t)(row0 + ai * 128 + m * 16) * F_ + col0;
;                 const f32x4 g0 = acc[ai][0][m][0], g1 = acc[ai][0][m][1], u0 = acc[ai][1][m][0], u1 = acc[ai][1][m][1];
;                 u32x4 w;
;                 w.x = pk2(siluf_(g0[0]) * u0[0], siluf_(g0[1]) * u0[1]); w.y = pk2(siluf_(g0[2]) * u0[2], siluf_(g0[3]) * u0[3]);
;                 w.z = pk2(siluf_(g1[0]) * u1[0], siluf_(g1[1]) * u1[1]); w.w = pk2(siluf_(g1[2]) * u1[2], siluf_(g1[3]) * u1[3]);
;                 *(u32x4*)rowp = w;
.LBB0_587:
	s_mov_b64 s[2:3], -1
	s_cmp_eq_u32 s58, 1
	v_lshl_add_u32 v130, s84, 8, v201
	s_cbranch_scc1 .LBB0_589
	v_mov_b32_e32 v146, 0xbfb8aa3b
	v_mov_b32_e32 v147, 0xbfb8aa3b
	v_readlane_b32 s2, v246, 17
	v_lshl_or_b32 v134, s83, 7, v170
	v_readlane_b32 s3, v246, 18
	v_ashrrev_i32_e32 v135, 31, v134
	s_movk_i32 s4, 0x2c00
	v_mov_b64_e32 v[132:133], s[2:3]
	v_mad_i64_i32 v[136:137], s[2:3], v130, s4, v[132:133]
	v_lshlrev_b64 v[134:135], 1, v[134:135]
	v_lshl_add_u64 v[140:141], v[136:137], 0, v[134:135]
	v_pk_mul_f32 v[142:143], v[126:127], v[146:147]
	v_exp_f32_e32 v142, v142
	v_exp_f32_e32 v143, v143
	v_add_f32_e32 v142, 1.0, v142
	v_add_f32_e32 v143, 1.0, v143
	v_rcp_f32_e32 v142, v142
	v_rcp_f32_e32 v143, v143
	v_pk_mul_f32 v[144:145], v[128:129], v[146:147]
	v_pk_mul_f32 v[142:143], v[126:127], v[142:143]
	v_pk_mul_f32 v[142:143], v[142:143], v[118:119]
	v_cvt_pk_bf16_f32 v136, v142, v143
	v_exp_f32_e32 v144, v144
	v_exp_f32_e32 v145, v145
	v_add_f32_e32 v144, 1.0, v144
	v_add_f32_e32 v145, 1.0, v145
	v_rcp_f32_e32 v144, v144
	v_rcp_f32_e32 v145, v145
	v_pk_mul_f32 v[142:143], v[122:123], v[146:147]
	v_pk_mul_f32 v[144:145], v[128:129], v[144:145]
	v_pk_mul_f32 v[144:145], v[144:145], v[120:121]
	v_cvt_pk_bf16_f32 v137, v144, v145
	v_exp_f32_e32 v142, v142
	v_exp_f32_e32 v143, v143
	v_add_f32_e32 v142, 1.0, v142
	v_add_f32_e32 v143, 1.0, v143
	v_rcp_f32_e32 v142, v142
	v_rcp_f32_e32 v143, v143
	v_pk_mul_f32 v[144:145], v[124:125], v[146:147]
	v_pk_mul_f32 v[142:143], v[122:123], v[142:143]
	v_pk_mul_f32 v[142:143], v[142:143], v[114:115]
	v_cvt_pk_bf16_f32 v138, v142, v143
	v_exp_f32_e32 v144, v144
	v_exp_f32_e32 v145, v145
	v_add_f32_e32 v144, 1.0, v144
	v_add_f32_e32 v145, 1.0, v145
	v_rcp_f32_e32 v144, v144
	v_rcp_f32_e32 v145, v145
	v_pk_mul_f32 v[142:143], v[110:111], v[146:147]
	v_pk_mul_f32 v[144:145], v[124:125], v[144:145]
	v_pk_mul_f32 v[144:145], v[144:145], v[116:117]
	v_cvt_pk_bf16_f32 v139, v144, v145
	v_or_b32_e32 v64, 16, v130
	global_store_dwordx4 v[140:141], v[136:139], off sc1
	s_nop 1
	v_mad_i64_i32 v[136:137], s[2:3], v64, s4, v[132:133]
	v_lshl_add_u64 v[140:141], v[136:137], 0, v[134:135]
	v_exp_f32_e32 v142, v142
	v_exp_f32_e32 v143, v143
	v_add_f32_e32 v142, 1.0, v142
	v_add_f32_e32 v143, 1.0, v143
	v_rcp_f32_e32 v142, v142
	v_rcp_f32_e32 v143, v143
	v_pk_mul_f32 v[144:145], v[112:113], v[146:147]
	v_pk_mul_f32 v[142:143], v[110:111], v[142:143]
	v_pk_mul_f32 v[142:143], v[142:143], v[102:103]
	v_cvt_pk_bf16_f32 v136, v142, v143
	v_exp_f32_e32 v144, v144
	v_exp_f32_e32 v145, v145
	v_add_f32_e32 v144, 1.0, v144
	v_add_f32_e32 v145, 1.0, v145
	v_rcp_f32_e32 v144, v144
	v_rcp_f32_e32 v145, v145
	v_pk_mul_f32 v[142:143], v[106:107], v[146:147]
	v_pk_mul_f32 v[144:145], v[112:113], v[144:145]
	v_pk_mul_f32 v[144:145], v[144:145], v[104:105]
	v_cvt_pk_bf16_f32 v137, v144, v145
	v_exp_f32_e32 v142, v142
	v_exp_f32_e32 v143, v143
	v_add_f32_e32 v142, 1.0, v142
	v_add_f32_e32 v143, 1.0, v143
	v_rcp_f32_e32 v142, v142
	v_rcp_f32_e32 v143, v143
	v_pk_mul_f32 v[144:145], v[108:109], v[146:147]
	v_pk_mul_f32 v[142:143], v[106:107], v[142:143]
	v_pk_mul_f32 v[142:143], v[142:143], v[98:99]
	v_cvt_pk_bf16_f32 v138, v142, v143
	v_exp_f32_e32 v144, v144
	v_exp_f32_e32 v145, v145
	v_add_f32_e32 v144, 1.0, v144
	v_add_f32_e32 v145, 1.0, v145
	v_rcp_f32_e32 v144, v144
	v_rcp_f32_e32 v145, v145
	v_pk_mul_f32 v[142:143], v[94:95], v[146:147]
	v_pk_mul_f32 v[144:145], v[108:109], v[144:145]
	v_pk_mul_f32 v[144:145], v[144:145], v[100:101]
	v_cvt_pk_bf16_f32 v139, v144, v145
	v_or_b32_e32 v64, 32, v130
	global_store_dwordx4 v[140:141], v[136:139], off sc1
	s_nop 1
	v_mad_i64_i32 v[136:137], s[2:3], v64, s4, v[132:133]
	v_lshl_add_u64 v[140:141], v[136:137], 0, v[134:135]
	v_exp_f32_e32 v142, v142
	v_exp_f32_e32 v143, v143
	v_add_f32_e32 v142, 1.0, v142
	v_add_f32_e32 v143, 1.0, v143
	v_rcp_f32_e32 v142, v142
	v_rcp_f32_e32 v143, v143
	v_pk_mul_f32 v[144:145], v[96:97], v[146:147]
	v_pk_mul_f32 v[142:143], v[94:95], v[142:143]
	v_pk_mul_f32 v[142:143], v[142:143], v[86:87]
	v_cvt_pk_bf16_f32 v136, v142, v143
	v_exp_f32_e32 v144, v144
	v_exp_f32_e32 v145, v145
	v_add_f32_e32 v144, 1.0, v144
	v_add_f32_e32 v145, 1.0, v145
	v_rcp_f32_e32 v144, v144
	v_rcp_f32_e32 v145, v145
	v_pk_mul_f32 v[142:143], v[90:91], v[146:147]
	v_pk_mul_f32 v[144:145], v[96:97], v[144:145]
	v_pk_mul_f32 v[144:145], v[144:145], v[88:89]
	v_cvt_pk_bf16_f32 v137, v144, v145
	v_exp_f32_e32 v142, v142
	v_exp_f32_e32 v143, v143
	v_add_f32_e32 v142, 1.0, v142
	v_add_f32_e32 v143, 1.0, v143
	v_rcp_f32_e32 v142, v142
	v_rcp_f32_e32 v143, v143
	v_pk_mul_f32 v[144:145], v[92:93], v[146:147]
	v_pk_mul_f32 v[142:143], v[90:91], v[142:143]
	v_pk_mul_f32 v[142:143], v[142:143], v[78:79]
	v_cvt_pk_bf16_f32 v138, v142, v143
	v_exp_f32_e32 v144, v144
	v_exp_f32_e32 v145, v145
	v_add_f32_e32 v144, 1.0, v144
	v_add_f32_e32 v145, 1.0, v145
	v_rcp_f32_e32 v144, v144
	v_rcp_f32_e32 v145, v145
	v_pk_mul_f32 v[142:143], v[82:83], v[146:147]
	v_pk_mul_f32 v[144:145], v[92:93], v[144:145]
	v_pk_mul_f32 v[144:145], v[144:145], v[80:81]
	v_cvt_pk_bf16_f32 v139, v144, v145
	v_or_b32_e32 v64, 48, v130
	global_store_dwordx4 v[140:141], v[136:139], off sc1
	s_nop 1
	v_mad_i64_i32 v[136:137], s[2:3], v64, s4, v[132:133]
	v_lshl_add_u64 v[140:141], v[136:137], 0, v[134:135]
	v_exp_f32_e32 v142, v142
	v_exp_f32_e32 v143, v143
	v_add_f32_e32 v142, 1.0, v142
	v_add_f32_e32 v143, 1.0, v143
	v_rcp_f32_e32 v142, v142
	v_rcp_f32_e32 v143, v143
	v_pk_mul_f32 v[144:145], v[84:85], v[146:147]
	v_pk_mul_f32 v[142:143], v[82:83], v[142:143]
	v_pk_mul_f32 v[142:143], v[142:143], v[70:71]
; __device__ __forceinline__ unsigned pk2(float lo, float hi) { unsigned r; asm volatile("v_cvt_pk_bf16_f32 %0, %1, %2" : "=v"(r) : "v"(lo), "v"(hi)); return r; }
; __device__ __forceinline__ float siluf_(float x) { return x * sigmoidf_(x); }
;     __device__ __forceinline__ void operator()(const f32x4 (&acc)[2][2][4][2], const pg8::Unit& u, int wr, int wc, int fr, int fq) const {
;     ...
;                 bf16_t* rowp = H + (size_t)(row0 + ai * 128 + m * 16) * F_ + col0;
;                 const f32x4 g0 = acc[ai][0][m][0], g1 = acc[ai][0][m][1], u0 = acc[ai][1][m][0], u1 = acc[ai][1][m][1];
;                 u32x4 w;
;                 w.x = pk2(siluf_(g0[0]) * u0[0], siluf_(g0[1]) * u0[1]); w.y = pk2(siluf_(g0[2]) * u0[2], siluf_(g0[3]) * u0[3]);
;                 w.z = pk2(siluf_(g1[0]) * u1[0], siluf_(g1[1]) * u1[1]); w.w = pk2(siluf_(g1[2]) * u1[2], siluf_(g1[3]) * u1[3]);
;                 *(u32x4*)rowp = w;
	v_cvt_pk_bf16_f32 v136, v142, v143
	v_exp_f32_e32 v144, v144
	v_exp_f32_e32 v145, v145
	v_add_f32_e32 v144, 1.0, v144
	v_add_f32_e32 v145, 1.0, v145
	v_rcp_f32_e32 v144, v144
	v_rcp_f32_e32 v145, v145
	v_pk_mul_f32 v[142:143], v[74:75], v[146:147]
	v_pk_mul_f32 v[144:145], v[84:85], v[144:145]
	v_pk_mul_f32 v[144:145], v[144:145], v[72:73]
	v_cvt_pk_bf16_f32 v137, v144, v145
	v_exp_f32_e32 v142, v142
	v_exp_f32_e32 v143, v143
	v_add_f32_e32 v142, 1.0, v142
	v_add_f32_e32 v143, 1.0, v143
	v_rcp_f32_e32 v142, v142
	v_rcp_f32_e32 v143, v143
	v_pk_mul_f32 v[144:145], v[76:77], v[146:147]
	v_pk_mul_f32 v[142:143], v[74:75], v[142:143]
	v_pk_mul_f32 v[142:143], v[142:143], v[66:67]
	v_cvt_pk_bf16_f32 v138, v142, v143
	v_exp_f32_e32 v144, v144
	v_exp_f32_e32 v145, v145
	v_add_f32_e32 v144, 1.0, v144
	v_add_f32_e32 v145, 1.0, v145
	v_rcp_f32_e32 v144, v144
	v_rcp_f32_e32 v145, v145
	v_pk_mul_f32 v[142:143], v[60:61], v[146:147]
	v_pk_mul_f32 v[144:145], v[76:77], v[144:145]
	v_pk_mul_f32 v[144:145], v[144:145], v[68:69]
	v_cvt_pk_bf16_f32 v139, v144, v145
	v_add_u32_e32 v64, 0x80, v130
	global_store_dwordx4 v[140:141], v[136:139], off sc1
	s_nop 1
	v_mad_i64_i32 v[136:137], s[2:3], v64, s4, v[132:133]
	v_lshl_add_u64 v[140:141], v[136:137], 0, v[134:135]
	v_exp_f32_e32 v142, v142
	v_exp_f32_e32 v143, v143
	v_add_f32_e32 v142, 1.0, v142
	v_add_f32_e32 v143, 1.0, v143
	v_rcp_f32_e32 v142, v142
	v_rcp_f32_e32 v143, v143
	v_pk_mul_f32 v[144:145], v[62:63], v[146:147]
	v_pk_mul_f32 v[142:143], v[60:61], v[142:143]
	v_pk_mul_f32 v[142:143], v[142:143], v[52:53]
	v_cvt_pk_bf16_f32 v136, v142, v143
	v_exp_f32_e32 v144, v144
	v_exp_f32_e32 v145, v145
	v_add_f32_e32 v144, 1.0, v144
	v_add_f32_e32 v145, 1.0, v145
	v_rcp_f32_e32 v144, v144
	v_rcp_f32_e32 v145, v145
	v_pk_mul_f32 v[142:143], v[56:57], v[146:147]
	v_pk_mul_f32 v[144:145], v[62:63], v[144:145]
	v_pk_mul_f32 v[144:145], v[144:145], v[54:55]
	v_cvt_pk_bf16_f32 v137, v144, v145
	v_exp_f32_e32 v142, v142
	v_exp_f32_e32 v143, v143
	v_add_f32_e32 v142, 1.0, v142
	v_add_f32_e32 v143, 1.0, v143
	v_rcp_f32_e32 v142, v142
	v_rcp_f32_e32 v143, v143
	v_pk_mul_f32 v[144:145], v[58:59], v[146:147]
	v_pk_mul_f32 v[142:143], v[56:57], v[142:143]
	v_pk_mul_f32 v[142:143], v[142:143], v[48:49]
	v_cvt_pk_bf16_f32 v138, v142, v143
	v_exp_f32_e32 v144, v144
	v_exp_f32_e32 v145, v145
	v_add_f32_e32 v144, 1.0, v144
	v_add_f32_e32 v145, 1.0, v145
	v_rcp_f32_e32 v144, v144
	v_rcp_f32_e32 v145, v145
	v_pk_mul_f32 v[142:143], v[44:45], v[146:147]
	v_pk_mul_f32 v[144:145], v[58:59], v[144:145]
	v_pk_mul_f32 v[144:145], v[144:145], v[50:51]
	v_cvt_pk_bf16_f32 v139, v144, v145
	v_add_u32_e32 v64, 0x90, v130
	global_store_dwordx4 v[140:141], v[136:139], off sc1
	s_nop 1
	v_mad_i64_i32 v[136:137], s[2:3], v64, s4, v[132:133]
	v_lshl_add_u64 v[140:141], v[136:137], 0, v[134:135]
	v_exp_f32_e32 v142, v142
	v_exp_f32_e32 v143, v143
	v_add_f32_e32 v142, 1.0, v142
	v_add_f32_e32 v143, 1.0, v143
	v_rcp_f32_e32 v142, v142
	v_rcp_f32_e32 v143, v143
	v_pk_mul_f32 v[144:145], v[46:47], v[146:147]
	v_pk_mul_f32 v[142:143], v[44:45], v[142:143]
	v_pk_mul_f32 v[142:143], v[142:143], v[36:37]
	v_cvt_pk_bf16_f32 v136, v142, v143
	v_exp_f32_e32 v144, v144
	v_exp_f32_e32 v145, v145
	v_add_f32_e32 v144, 1.0, v144
	v_add_f32_e32 v145, 1.0, v145
	v_rcp_f32_e32 v144, v144
	v_rcp_f32_e32 v145, v145
	v_pk_mul_f32 v[142:143], v[40:41], v[146:147]
	v_pk_mul_f32 v[144:145], v[46:47], v[144:145]
	v_pk_mul_f32 v[144:145], v[144:145], v[38:39]
	v_cvt_pk_bf16_f32 v137, v144, v145
	v_exp_f32_e32 v142, v142
	v_exp_f32_e32 v143, v143
	v_add_f32_e32 v142, 1.0, v142
	v_add_f32_e32 v143, 1.0, v143
	v_rcp_f32_e32 v142, v142
	v_rcp_f32_e32 v143, v143
; __device__ __forceinline__ unsigned pk2(float lo, float hi) { unsigned r; asm volatile("v_cvt_pk_bf16_f32 %0, %1, %2" : "=v"(r) : "v"(lo), "v"(hi)); return r; }
; __device__ __forceinline__ float siluf_(float x) { return x * sigmoidf_(x); }
;     __device__ __forceinline__ void operator()(const f32x4 (&acc)[2][2][4][2], const pg8::Unit& u, int wr, int wc, int fr, int fq) const {
;     ...
;                 bf16_t* rowp = H + (size_t)(row0 + ai * 128 + m * 16) * F_ + col0;
;                 const f32x4 g0 = acc[ai][0][m][0], g1 = acc[ai][0][m][1], u0 = acc[ai][1][m][0], u1 = acc[ai][1][m][1];
;                 u32x4 w;
;                 w.x = pk2(siluf_(g0[0]) * u0[0], siluf_(g0[1]) * u0[1]); w.y = pk2(siluf_(g0[2]) * u0[2], siluf_(g0[3]) * u0[3]);
;                 w.z = pk2(siluf_(g1[0]) * u1[0], siluf_(g1[1]) * u1[1]); w.w = pk2(siluf_(g1[2]) * u1[2], siluf_(g1[3]) * u1[3]);
;                 *(u32x4*)rowp = w;
	v_pk_mul_f32 v[144:145], v[42:43], v[146:147]
	v_pk_mul_f32 v[142:143], v[40:41], v[142:143]
	v_pk_mul_f32 v[142:143], v[142:143], v[32:33]
	v_cvt_pk_bf16_f32 v138, v142, v143
	v_exp_f32_e32 v144, v144
	v_exp_f32_e32 v145, v145
	v_add_f32_e32 v144, 1.0, v144
	v_add_f32_e32 v145, 1.0, v145
	v_rcp_f32_e32 v144, v144
	v_rcp_f32_e32 v145, v145
	v_pk_mul_f32 v[142:143], v[28:29], v[146:147]
	v_pk_mul_f32 v[144:145], v[42:43], v[144:145]
	v_pk_mul_f32 v[144:145], v[144:145], v[34:35]
	v_cvt_pk_bf16_f32 v139, v144, v145
	v_add_u32_e32 v64, 0xa0, v130
	global_store_dwordx4 v[140:141], v[136:139], off sc1
	s_nop 1
	v_mad_i64_i32 v[136:137], s[2:3], v64, s4, v[132:133]
	v_lshl_add_u64 v[140:141], v[136:137], 0, v[134:135]
	v_exp_f32_e32 v142, v142
	v_exp_f32_e32 v143, v143
	v_add_f32_e32 v142, 1.0, v142
	v_add_f32_e32 v143, 1.0, v143
	v_rcp_f32_e32 v142, v142
	v_rcp_f32_e32 v143, v143
	v_pk_mul_f32 v[144:145], v[30:31], v[146:147]
	v_pk_mul_f32 v[142:143], v[28:29], v[142:143]
	v_pk_mul_f32 v[142:143], v[142:143], v[16:17]
	v_cvt_pk_bf16_f32 v136, v142, v143
	v_exp_f32_e32 v144, v144
	v_exp_f32_e32 v145, v145
	v_add_f32_e32 v144, 1.0, v144
	v_add_f32_e32 v145, 1.0, v145
	v_rcp_f32_e32 v144, v144
	v_rcp_f32_e32 v145, v145
	v_pk_mul_f32 v[142:143], v[24:25], v[146:147]
	v_pk_mul_f32 v[144:145], v[30:31], v[144:145]
	v_pk_mul_f32 v[144:145], v[144:145], v[18:19]
	v_cvt_pk_bf16_f32 v137, v144, v145
	v_exp_f32_e32 v142, v142
	v_exp_f32_e32 v143, v143
	v_add_f32_e32 v142, 1.0, v142
	v_add_f32_e32 v143, 1.0, v143
	v_rcp_f32_e32 v142, v142
	v_rcp_f32_e32 v143, v143
	v_pk_mul_f32 v[144:145], v[26:27], v[146:147]
	v_pk_mul_f32 v[142:143], v[24:25], v[142:143]
	v_pk_mul_f32 v[142:143], v[142:143], v[12:13]
	v_cvt_pk_bf16_f32 v138, v142, v143
	v_exp_f32_e32 v144, v144
	v_exp_f32_e32 v145, v145
	v_add_f32_e32 v144, 1.0, v144
	v_add_f32_e32 v145, 1.0, v145
	v_rcp_f32_e32 v144, v144
	v_rcp_f32_e32 v145, v145
	v_pk_mul_f32 v[142:143], v[20:21], v[146:147]
	v_pk_mul_f32 v[144:145], v[26:27], v[144:145]
	v_pk_mul_f32 v[144:145], v[144:145], v[14:15]
	v_cvt_pk_bf16_f32 v139, v144, v145
	v_add_u32_e32 v64, 0xb0, v130
	v_mad_i64_i32 v[132:133], s[2:3], v64, s4, v[132:133]
	global_store_dwordx4 v[140:141], v[136:139], off sc1
	s_nop 1
	s_mov_b64 s[2:3], 0
	v_lshl_add_u64 v[136:137], v[132:133], 0, v[134:135]
	v_exp_f32_e32 v142, v142
	v_exp_f32_e32 v143, v143
	v_add_f32_e32 v142, 1.0, v142
	v_add_f32_e32 v143, 1.0, v143
	v_rcp_f32_e32 v142, v142
	v_rcp_f32_e32 v143, v143
	v_pk_mul_f32 v[144:145], v[22:23], v[146:147]
	v_pk_mul_f32 v[142:143], v[20:21], v[142:143]
	v_pk_mul_f32 v[142:143], v[142:143], v[4:5]
	v_cvt_pk_bf16_f32 v132, v142, v143
	v_exp_f32_e32 v144, v144
	v_exp_f32_e32 v145, v145
	v_add_f32_e32 v144, 1.0, v144
	v_add_f32_e32 v145, 1.0, v145
	v_rcp_f32_e32 v144, v144
	v_rcp_f32_e32 v145, v145
	v_pk_mul_f32 v[142:143], v[8:9], v[146:147]
	v_pk_mul_f32 v[144:145], v[22:23], v[144:145]
	v_pk_mul_f32 v[144:145], v[144:145], v[6:7]
	v_cvt_pk_bf16_f32 v133, v144, v145
	v_exp_f32_e32 v142, v142
	v_exp_f32_e32 v143, v143
	v_add_f32_e32 v142, 1.0, v142
	v_add_f32_e32 v143, 1.0, v143
	v_rcp_f32_e32 v142, v142
	v_rcp_f32_e32 v143, v143
	v_pk_mul_f32 v[144:145], v[10:11], v[146:147]
	v_pk_mul_f32 v[142:143], v[8:9], v[142:143]
	v_pk_mul_f32 v[142:143], v[142:143], v[0:1]
	v_cvt_pk_bf16_f32 v134, v142, v143
	v_exp_f32_e32 v144, v144
	v_exp_f32_e32 v145, v145
	v_add_f32_e32 v144, 1.0, v144
	v_add_f32_e32 v145, 1.0, v145
	v_rcp_f32_e32 v144, v144
	v_rcp_f32_e32 v145, v145
	s_nop 0
	v_pk_mul_f32 v[144:145], v[10:11], v[144:145]
	v_pk_mul_f32 v[144:145], v[144:145], v[2:3]
	v_cvt_pk_bf16_f32 v135, v144, v145
	global_store_dwordx4 v[136:137], v[132:135], off sc1
	s_nop 1
